# hand-written packed residual epilogue (out-proj/down): 16 loads up front, per-row-group counted waits, v_pk_add + v_pk_fma sum of squares, batched row reduction; packed producers kept one instruction
# baseline (speedup 1.0000x reference)
; #define LAS __attribute__((address_space(3)))
; __device__ __forceinline__ unsigned cvt_pk_bf16(float lo, float hi) { unsigned r; asm volatile("v_cvt_pk_bf16_f32 %0, %1, %2" : "=v"(r) : "v"(lo), "v"(hi)); return r; }
;     __device__ __forceinline__ void operator()(const f32x4 (&acc)[2][2][4][2], const Unit& u, int wr, int wc, int fr, int fq) const {
;         const int row0 = u.pm * BM + wr * 64 + fr, col0 = u.pn * BM + wc * 32 + 8 * fq;
;         LAS float* part = (LAS float*)(lds + PART_OFF);
;         u32x4 bb[2][4][2];
; #pragma unroll
;         for (int ai = 0; ai < 2; ++ai)
; #pragma unroll
;             for (int m = 0; m < 4; ++m)
; #pragma unroll
;                 for (int bj = 0; bj < 2; ++bj) bb[ai][m][bj] = *(const u32x4*)(xb + (size_t)(row0 + ai * HALF + m * 16) * D + col0 + bj * HALF);
; #pragma unroll
;         for (int ai = 0; ai < 2; ++ai)
; #pragma unroll
;             for (int m = 0; m < 4; ++m) { const size_t off = (size_t)(row0 + ai * HALF + m * 16) * D + col0; float sq = 0.f;
; #pragma unroll
;                 for (int bj = 0; bj < 2; ++bj) { const u32x4 b = bb[ai][m][bj];
;                     const f32x4 v0 = acc[ai][bj][m][0] + (f32x4){bflo(b.x), bfhi(b.x), bflo(b.y), bfhi(b.y)}, v1 = acc[ai][bj][m][1] + (f32x4){bflo(b.z), bfhi(b.z), bflo(b.w), bfhi(b.w)};
;                     u32x4 w; w.x = cvt_pk_bf16(v0[0], v0[1]); w.y = cvt_pk_bf16(v0[2], v0[3]); w.z = cvt_pk_bf16(v1[0], v1[1]); w.w = cvt_pk_bf16(v1[2], v1[3]);
;                     *(u32x4*)(xb + off + bj * HALF) = w;
;                     const float r0 = bflo(w.x), r1 = bfhi(w.x), r2 = bflo(w.y), r3 = bfhi(w.y), r4 = bflo(w.z), r5 = bfhi(w.z), r6 = bflo(w.w), r7 = bfhi(w.w);
;                     sq += ((r0 * r0 + r1 * r1) + (r2 * r2 + r3 * r3)) + ((r4 * r4 + r5 * r5) + (r6 * r6 + r7 * r7)); }
.LBB0_154:
	s_lshl_b32 s35, s35, 8
	v_add_u32_e32 v207, s35, v242
	v_lshl_or_b32 v206, s34, 8, v243
	v_lshlrev_b32_e32 v207, 11, v207
	v_lshl_add_u32 v207, v206, 1, v207
	s_mov_b32 s4, 0xffff0000
	v_mov_b32_e32 v206, v207
	global_load_dwordx4 v[108:111], v207, s[18:19]
	global_load_dwordx4 v[120:123], v207, s[18:19] offset:256
	v_add_u32_e32 v207, 0x8000, v207
	global_load_dwordx4 v[128:131], v207, s[18:19]
	global_load_dwordx4 v[132:135], v207, s[18:19] offset:256
	v_add_u32_e32 v207, 0x8000, v207
	global_load_dwordx4 v[136:139], v207, s[18:19]
	global_load_dwordx4 v[144:147], v207, s[18:19] offset:256
	v_add_u32_e32 v207, 0x8000, v207
	global_load_dwordx4 v[148:151], v207, s[18:19]
	global_load_dwordx4 v[152:155], v207, s[18:19] offset:256
	v_add_u32_e32 v207, 0x28000, v207
	global_load_dwordx4 v[156:159], v207, s[18:19]
	global_load_dwordx4 v[160:163], v207, s[18:19] offset:256
	v_add_u32_e32 v207, 0x8000, v207
	global_load_dwordx4 v[164:167], v207, s[18:19]
	global_load_dwordx4 v[176:179], v207, s[18:19] offset:256
	v_add_u32_e32 v207, 0x8000, v207
	global_load_dwordx4 v[180:183], v207, s[18:19]
	global_load_dwordx4 v[184:187], v207, s[18:19] offset:256
	v_add_u32_e32 v207, 0x8000, v207
	global_load_dwordx4 v[188:191], v207, s[18:19]
	global_load_dwordx4 v[202:205], v207, s[18:19] offset:256
	v_mov_b32_e32 v216, 0
	v_mov_b32_e32 v217, 0
	v_mov_b32_e32 v218, 0
	v_mov_b32_e32 v219, 0
	v_mov_b32_e32 v248, 0
	v_mov_b32_e32 v249, 0
	v_mov_b32_e32 v250, 0
	v_mov_b32_e32 v251, 0
	v_mov_b32_e32 v252, 0
	v_mov_b32_e32 v253, 0
	v_mov_b32_e32 v2, 0
	v_mov_b32_e32 v3, 0
	v_mov_b32_e32 v192, 0
	v_mov_b32_e32 v193, 0
	s_waitcnt vmcnt(14)
	v_lshlrev_b32_e32 v208, 16, v108
	v_and_b32_e32 v209, s4, v108
	v_pk_add_f32 v[172:173], v[172:173], v[208:209]
	v_lshlrev_b32_e32 v210, 16, v109
	v_and_b32_e32 v211, s4, v109
	v_pk_add_f32 v[174:175], v[174:175], v[210:211]
	v_lshlrev_b32_e32 v208, 16, v110
	v_and_b32_e32 v209, s4, v110
	v_pk_add_f32 v[168:169], v[168:169], v[208:209]
	v_lshlrev_b32_e32 v210, 16, v111
	v_and_b32_e32 v211, s4, v111
	v_pk_add_f32 v[170:171], v[170:171], v[210:211]
	v_cvt_pk_bf16_f32 v108, v172, v173
	v_cvt_pk_bf16_f32 v109, v174, v175
	v_cvt_pk_bf16_f32 v110, v168, v169
	v_cvt_pk_bf16_f32 v111, v170, v171
	v_lshlrev_b32_e32 v212, 16, v108
	v_and_b32_e32 v213, s4, v108
	v_pk_fma_f32 v[216:217], v[212:213], v[212:213], v[216:217]
	v_lshlrev_b32_e32 v214, 16, v109
	v_and_b32_e32 v215, s4, v109
	v_pk_fma_f32 v[216:217], v[214:215], v[214:215], v[216:217]
	v_lshlrev_b32_e32 v212, 16, v110
	v_and_b32_e32 v213, s4, v110
	v_pk_fma_f32 v[216:217], v[212:213], v[212:213], v[216:217]
	v_lshlrev_b32_e32 v214, 16, v111
	v_and_b32_e32 v215, s4, v111
	v_pk_fma_f32 v[216:217], v[214:215], v[214:215], v[216:217]
	global_store_dwordx4 v206, v[108:111], s[18:19]
	v_lshlrev_b32_e32 v208, 16, v120
	v_and_b32_e32 v209, s4, v120
	v_pk_add_f32 v[140:141], v[140:141], v[208:209]
	v_lshlrev_b32_e32 v210, 16, v121
	v_and_b32_e32 v211, s4, v121
	v_pk_add_f32 v[142:143], v[142:143], v[210:211]
	v_lshlrev_b32_e32 v208, 16, v122
	v_and_b32_e32 v209, s4, v122
	v_pk_add_f32 v[124:125], v[124:125], v[208:209]
	v_lshlrev_b32_e32 v210, 16, v123
	v_and_b32_e32 v211, s4, v123
	v_pk_add_f32 v[126:127], v[126:127], v[210:211]
	v_cvt_pk_bf16_f32 v120, v140, v141
	v_cvt_pk_bf16_f32 v121, v142, v143
	v_cvt_pk_bf16_f32 v122, v124, v125
	v_cvt_pk_bf16_f32 v123, v126, v127
	v_lshlrev_b32_e32 v212, 16, v120
	v_and_b32_e32 v213, s4, v120
	v_pk_fma_f32 v[216:217], v[212:213], v[212:213], v[216:217]
	v_lshlrev_b32_e32 v214, 16, v121
	v_and_b32_e32 v215, s4, v121
	v_pk_fma_f32 v[216:217], v[214:215], v[214:215], v[216:217]
	v_lshlrev_b32_e32 v212, 16, v122
	v_and_b32_e32 v213, s4, v122
	v_pk_fma_f32 v[216:217], v[212:213], v[212:213], v[216:217]
	v_lshlrev_b32_e32 v214, 16, v123
	v_and_b32_e32 v215, s4, v123
	v_pk_fma_f32 v[216:217], v[214:215], v[214:215], v[216:217]
	global_store_dwordx4 v206, v[120:123], s[18:19] offset:256
	v_add_u32_e32 v206, 0x8000, v206
	s_waitcnt vmcnt(14)
	v_mov_b32_e32 v172, 0
	v_mov_b32_e32 v173, 0
	v_lshlrev_b32_e32 v208, 16, v128
	v_and_b32_e32 v209, s4, v128
	v_pk_add_f32 v[116:117], v[116:117], v[208:209]
	v_lshlrev_b32_e32 v210, 16, v129
	v_and_b32_e32 v211, s4, v129
	v_pk_add_f32 v[118:119], v[118:119], v[210:211]
	v_lshlrev_b32_e32 v208, 16, v130
	v_and_b32_e32 v209, s4, v130
	v_pk_add_f32 v[112:113], v[112:113], v[208:209]
	v_lshlrev_b32_e32 v210, 16, v131
	v_and_b32_e32 v211, s4, v131
	v_pk_add_f32 v[114:115], v[114:115], v[210:211]
	v_cvt_pk_bf16_f32 v128, v116, v117
	v_cvt_pk_bf16_f32 v129, v118, v119
	v_cvt_pk_bf16_f32 v130, v112, v113
	v_cvt_pk_bf16_f32 v131, v114, v115
	v_lshlrev_b32_e32 v212, 16, v128
	v_and_b32_e32 v213, s4, v128
	v_pk_fma_f32 v[218:219], v[212:213], v[212:213], v[218:219]
	v_lshlrev_b32_e32 v214, 16, v129
	v_and_b32_e32 v215, s4, v129
	v_pk_fma_f32 v[218:219], v[214:215], v[214:215], v[218:219]
	v_lshlrev_b32_e32 v212, 16, v130
	v_and_b32_e32 v213, s4, v130
	v_pk_fma_f32 v[218:219], v[212:213], v[212:213], v[218:219]
	v_lshlrev_b32_e32 v214, 16, v131
	v_and_b32_e32 v215, s4, v131
	v_pk_fma_f32 v[218:219], v[214:215], v[214:215], v[218:219]
	global_store_dwordx4 v206, v[128:131], s[18:19]
	v_lshlrev_b32_e32 v208, 16, v132
	v_and_b32_e32 v209, s4, v132
	v_pk_add_f32 v[104:105], v[104:105], v[208:209]
	v_lshlrev_b32_e32 v210, 16, v133
	v_and_b32_e32 v211, s4, v133
	v_pk_add_f32 v[106:107], v[106:107], v[210:211]
	v_lshlrev_b32_e32 v208, 16, v134
	v_and_b32_e32 v209, s4, v134
	v_pk_add_f32 v[100:101], v[100:101], v[208:209]
	v_lshlrev_b32_e32 v210, 16, v135
	v_and_b32_e32 v211, s4, v135
	v_pk_add_f32 v[102:103], v[102:103], v[210:211]
	v_cvt_pk_bf16_f32 v132, v104, v105
	v_cvt_pk_bf16_f32 v133, v106, v107
	v_cvt_pk_bf16_f32 v134, v100, v101
	v_cvt_pk_bf16_f32 v135, v102, v103
	v_lshlrev_b32_e32 v212, 16, v132
	v_and_b32_e32 v213, s4, v132
	v_pk_fma_f32 v[218:219], v[212:213], v[212:213], v[218:219]
	v_lshlrev_b32_e32 v214, 16, v133
	v_and_b32_e32 v215, s4, v133
	v_pk_fma_f32 v[218:219], v[214:215], v[214:215], v[218:219]
	v_lshlrev_b32_e32 v212, 16, v134
	v_and_b32_e32 v213, s4, v134
	v_pk_fma_f32 v[218:219], v[212:213], v[212:213], v[218:219]
	v_lshlrev_b32_e32 v214, 16, v135
	v_and_b32_e32 v215, s4, v135
	v_pk_fma_f32 v[218:219], v[214:215], v[214:215], v[218:219]
	global_store_dwordx4 v206, v[132:135], s[18:19] offset:256
	v_add_u32_e32 v206, 0x8000, v206
	s_waitcnt vmcnt(14)
; __device__ __forceinline__ unsigned cvt_pk_bf16(float lo, float hi) { unsigned r; asm volatile("v_cvt_pk_bf16_f32 %0, %1, %2" : "=v"(r) : "v"(lo), "v"(hi)); return r; }
;     __device__ __forceinline__ void operator()(const f32x4 (&acc)[2][2][4][2], const Unit& u, int wr, int wc, int fr, int fq) const {
;     ...
;             for (int m = 0; m < 4; ++m) { const size_t off = (size_t)(row0 + ai * HALF + m * 16) * D + col0; float sq = 0.f;
; #pragma unroll
;                 for (int bj = 0; bj < 2; ++bj) { const u32x4 b = bb[ai][m][bj];
;                     const f32x4 v0 = acc[ai][bj][m][0] + (f32x4){bflo(b.x), bfhi(b.x), bflo(b.y), bfhi(b.y)}, v1 = acc[ai][bj][m][1] + (f32x4){bflo(b.z), bfhi(b.z), bflo(b.w), bfhi(b.w)};
;                     u32x4 w; w.x = cvt_pk_bf16(v0[0], v0[1]); w.y = cvt_pk_bf16(v0[2], v0[3]); w.z = cvt_pk_bf16(v1[0], v1[1]); w.w = cvt_pk_bf16(v1[2], v1[3]);
;                     *(u32x4*)(xb + off + bj * HALF) = w;
;                     const float r0 = bflo(w.x), r1 = bfhi(w.x), r2 = bflo(w.y), r3 = bfhi(w.y), r4 = bflo(w.z), r5 = bfhi(w.z), r6 = bflo(w.w), r7 = bfhi(w.w);
;                     sq += ((r0 * r0 + r1 * r1) + (r2 * r2 + r3 * r3)) + ((r4 * r4 + r5 * r5) + (r6 * r6 + r7 * r7)); }
	v_lshlrev_b32_e32 v208, 16, v136
	v_and_b32_e32 v209, s4, v136
	v_pk_add_f32 v[96:97], v[96:97], v[208:209]
	v_lshlrev_b32_e32 v210, 16, v137
	v_and_b32_e32 v211, s4, v137
	v_pk_add_f32 v[98:99], v[98:99], v[210:211]
	v_lshlrev_b32_e32 v208, 16, v138
	v_and_b32_e32 v209, s4, v138
	v_pk_add_f32 v[92:93], v[92:93], v[208:209]
	v_lshlrev_b32_e32 v210, 16, v139
	v_and_b32_e32 v211, s4, v139
	v_pk_add_f32 v[94:95], v[94:95], v[210:211]
	v_cvt_pk_bf16_f32 v136, v96, v97
	v_cvt_pk_bf16_f32 v137, v98, v99
	v_cvt_pk_bf16_f32 v138, v92, v93
	v_cvt_pk_bf16_f32 v139, v94, v95
	v_lshlrev_b32_e32 v212, 16, v136
	v_and_b32_e32 v213, s4, v136
	v_pk_fma_f32 v[248:249], v[212:213], v[212:213], v[248:249]
	v_lshlrev_b32_e32 v214, 16, v137
	v_and_b32_e32 v215, s4, v137
	v_pk_fma_f32 v[248:249], v[214:215], v[214:215], v[248:249]
	v_lshlrev_b32_e32 v212, 16, v138
	v_and_b32_e32 v213, s4, v138
	v_pk_fma_f32 v[248:249], v[212:213], v[212:213], v[248:249]
	v_lshlrev_b32_e32 v214, 16, v139
	v_and_b32_e32 v215, s4, v139
	v_pk_fma_f32 v[248:249], v[214:215], v[214:215], v[248:249]
	global_store_dwordx4 v206, v[136:139], s[18:19]
	v_lshlrev_b32_e32 v208, 16, v144
	v_and_b32_e32 v209, s4, v144
	v_pk_add_f32 v[88:89], v[88:89], v[208:209]
	v_lshlrev_b32_e32 v210, 16, v145
	v_and_b32_e32 v211, s4, v145
	v_pk_add_f32 v[90:91], v[90:91], v[210:211]
	v_lshlrev_b32_e32 v208, 16, v146
	v_and_b32_e32 v209, s4, v146
	v_pk_add_f32 v[84:85], v[84:85], v[208:209]
	v_lshlrev_b32_e32 v210, 16, v147
	v_and_b32_e32 v211, s4, v147
	v_pk_add_f32 v[86:87], v[86:87], v[210:211]
	v_cvt_pk_bf16_f32 v144, v88, v89
	v_cvt_pk_bf16_f32 v145, v90, v91
	v_cvt_pk_bf16_f32 v146, v84, v85
	v_cvt_pk_bf16_f32 v147, v86, v87
	v_lshlrev_b32_e32 v212, 16, v144
	v_and_b32_e32 v213, s4, v144
	v_pk_fma_f32 v[248:249], v[212:213], v[212:213], v[248:249]
	v_lshlrev_b32_e32 v214, 16, v145
	v_and_b32_e32 v215, s4, v145
	v_pk_fma_f32 v[248:249], v[214:215], v[214:215], v[248:249]
	v_lshlrev_b32_e32 v212, 16, v146
	v_and_b32_e32 v213, s4, v146
	v_pk_fma_f32 v[248:249], v[212:213], v[212:213], v[248:249]
	v_lshlrev_b32_e32 v214, 16, v147
	v_and_b32_e32 v215, s4, v147
	v_pk_fma_f32 v[248:249], v[214:215], v[214:215], v[248:249]
	global_store_dwordx4 v206, v[144:147], s[18:19] offset:256
	v_add_u32_e32 v206, 0x8000, v206
	s_waitcnt vmcnt(14)
	v_lshlrev_b32_e32 v208, 16, v148
	v_and_b32_e32 v209, s4, v148
	v_pk_add_f32 v[80:81], v[80:81], v[208:209]
	v_lshlrev_b32_e32 v210, 16, v149
	v_and_b32_e32 v211, s4, v149
	v_pk_add_f32 v[82:83], v[82:83], v[210:211]
	v_lshlrev_b32_e32 v208, 16, v150
	v_and_b32_e32 v209, s4, v150
	v_pk_add_f32 v[76:77], v[76:77], v[208:209]
	v_lshlrev_b32_e32 v210, 16, v151
	v_and_b32_e32 v211, s4, v151
	v_pk_add_f32 v[78:79], v[78:79], v[210:211]
	v_cvt_pk_bf16_f32 v148, v80, v81
	v_cvt_pk_bf16_f32 v149, v82, v83
	v_cvt_pk_bf16_f32 v150, v76, v77
	v_cvt_pk_bf16_f32 v151, v78, v79
	v_lshlrev_b32_e32 v212, 16, v148
	v_and_b32_e32 v213, s4, v148
	v_pk_fma_f32 v[250:251], v[212:213], v[212:213], v[250:251]
	v_lshlrev_b32_e32 v214, 16, v149
	v_and_b32_e32 v215, s4, v149
	v_pk_fma_f32 v[250:251], v[214:215], v[214:215], v[250:251]
	v_lshlrev_b32_e32 v212, 16, v150
	v_and_b32_e32 v213, s4, v150
	v_pk_fma_f32 v[250:251], v[212:213], v[212:213], v[250:251]
	v_lshlrev_b32_e32 v214, 16, v151
	v_and_b32_e32 v215, s4, v151
	v_pk_fma_f32 v[250:251], v[214:215], v[214:215], v[250:251]
	global_store_dwordx4 v206, v[148:151], s[18:19]
	v_lshlrev_b32_e32 v208, 16, v152
	v_and_b32_e32 v209, s4, v152
	v_pk_add_f32 v[72:73], v[72:73], v[208:209]
	v_lshlrev_b32_e32 v210, 16, v153
	v_and_b32_e32 v211, s4, v153
	v_pk_add_f32 v[74:75], v[74:75], v[210:211]
	v_lshlrev_b32_e32 v208, 16, v154
	v_and_b32_e32 v209, s4, v154
	v_pk_add_f32 v[68:69], v[68:69], v[208:209]
	v_lshlrev_b32_e32 v210, 16, v155
	v_and_b32_e32 v211, s4, v155
	v_pk_add_f32 v[70:71], v[70:71], v[210:211]
	v_cvt_pk_bf16_f32 v152, v72, v73
	v_cvt_pk_bf16_f32 v153, v74, v75
	v_cvt_pk_bf16_f32 v154, v68, v69
	v_cvt_pk_bf16_f32 v155, v70, v71
	v_lshlrev_b32_e32 v212, 16, v152
	v_and_b32_e32 v213, s4, v152
	v_pk_fma_f32 v[250:251], v[212:213], v[212:213], v[250:251]
	v_lshlrev_b32_e32 v214, 16, v153
	v_and_b32_e32 v215, s4, v153
	v_pk_fma_f32 v[250:251], v[214:215], v[214:215], v[250:251]
	v_lshlrev_b32_e32 v212, 16, v154
	v_and_b32_e32 v213, s4, v154
	v_pk_fma_f32 v[250:251], v[212:213], v[212:213], v[250:251]
	v_lshlrev_b32_e32 v214, 16, v155
	v_and_b32_e32 v215, s4, v155
	v_pk_fma_f32 v[250:251], v[214:215], v[214:215], v[250:251]
	global_store_dwordx4 v206, v[152:155], s[18:19] offset:256
	v_add_u32_e32 v206, 0x28000, v206
	s_waitcnt vmcnt(14)
; __device__ __forceinline__ unsigned cvt_pk_bf16(float lo, float hi) { unsigned r; asm volatile("v_cvt_pk_bf16_f32 %0, %1, %2" : "=v"(r) : "v"(lo), "v"(hi)); return r; }
;     __device__ __forceinline__ void operator()(const f32x4 (&acc)[2][2][4][2], const Unit& u, int wr, int wc, int fr, int fq) const {
;     ...
;             for (int m = 0; m < 4; ++m) { const size_t off = (size_t)(row0 + ai * HALF + m * 16) * D + col0; float sq = 0.f;
; #pragma unroll
;                 for (int bj = 0; bj < 2; ++bj) { const u32x4 b = bb[ai][m][bj];
;                     const f32x4 v0 = acc[ai][bj][m][0] + (f32x4){bflo(b.x), bfhi(b.x), bflo(b.y), bfhi(b.y)}, v1 = acc[ai][bj][m][1] + (f32x4){bflo(b.z), bfhi(b.z), bflo(b.w), bfhi(b.w)};
;                     u32x4 w; w.x = cvt_pk_bf16(v0[0], v0[1]); w.y = cvt_pk_bf16(v0[2], v0[3]); w.z = cvt_pk_bf16(v1[0], v1[1]); w.w = cvt_pk_bf16(v1[2], v1[3]);
;                     *(u32x4*)(xb + off + bj * HALF) = w;
;                     const float r0 = bflo(w.x), r1 = bfhi(w.x), r2 = bflo(w.y), r3 = bfhi(w.y), r4 = bflo(w.z), r5 = bfhi(w.z), r6 = bflo(w.w), r7 = bfhi(w.w);
;                     sq += ((r0 * r0 + r1 * r1) + (r2 * r2 + r3 * r3)) + ((r4 * r4 + r5 * r5) + (r6 * r6 + r7 * r7)); }
	v_lshlrev_b32_e32 v208, 16, v156
	v_and_b32_e32 v209, s4, v156
	v_pk_add_f32 v[64:65], v[64:65], v[208:209]
	v_lshlrev_b32_e32 v210, 16, v157
	v_and_b32_e32 v211, s4, v157
	v_pk_add_f32 v[66:67], v[66:67], v[210:211]
	v_lshlrev_b32_e32 v208, 16, v158
	v_and_b32_e32 v209, s4, v158
	v_pk_add_f32 v[60:61], v[60:61], v[208:209]
	v_lshlrev_b32_e32 v210, 16, v159
	v_and_b32_e32 v211, s4, v159
	v_pk_add_f32 v[62:63], v[62:63], v[210:211]
	v_cvt_pk_bf16_f32 v156, v64, v65
	v_cvt_pk_bf16_f32 v157, v66, v67
	v_cvt_pk_bf16_f32 v158, v60, v61
	v_cvt_pk_bf16_f32 v159, v62, v63
	v_lshlrev_b32_e32 v212, 16, v156
	v_and_b32_e32 v213, s4, v156
	v_pk_fma_f32 v[252:253], v[212:213], v[212:213], v[252:253]
	v_lshlrev_b32_e32 v214, 16, v157
	v_and_b32_e32 v215, s4, v157
	v_pk_fma_f32 v[252:253], v[214:215], v[214:215], v[252:253]
	v_lshlrev_b32_e32 v212, 16, v158
	v_and_b32_e32 v213, s4, v158
	v_pk_fma_f32 v[252:253], v[212:213], v[212:213], v[252:253]
	v_lshlrev_b32_e32 v214, 16, v159
	v_and_b32_e32 v215, s4, v159
	v_pk_fma_f32 v[252:253], v[214:215], v[214:215], v[252:253]
	global_store_dwordx4 v206, v[156:159], s[18:19]
	v_lshlrev_b32_e32 v208, 16, v160
	v_and_b32_e32 v209, s4, v160
	v_pk_add_f32 v[56:57], v[56:57], v[208:209]
	v_lshlrev_b32_e32 v210, 16, v161
	v_and_b32_e32 v211, s4, v161
	v_pk_add_f32 v[58:59], v[58:59], v[210:211]
	v_lshlrev_b32_e32 v208, 16, v162
	v_and_b32_e32 v209, s4, v162
	v_pk_add_f32 v[52:53], v[52:53], v[208:209]
	v_lshlrev_b32_e32 v210, 16, v163
	v_and_b32_e32 v211, s4, v163
	v_pk_add_f32 v[54:55], v[54:55], v[210:211]
	v_cvt_pk_bf16_f32 v160, v56, v57
	v_cvt_pk_bf16_f32 v161, v58, v59
	v_cvt_pk_bf16_f32 v162, v52, v53
	v_cvt_pk_bf16_f32 v163, v54, v55
	v_lshlrev_b32_e32 v212, 16, v160
	v_and_b32_e32 v213, s4, v160
	v_pk_fma_f32 v[252:253], v[212:213], v[212:213], v[252:253]
	v_lshlrev_b32_e32 v214, 16, v161
	v_and_b32_e32 v215, s4, v161
	v_pk_fma_f32 v[252:253], v[214:215], v[214:215], v[252:253]
	v_lshlrev_b32_e32 v212, 16, v162
	v_and_b32_e32 v213, s4, v162
	v_pk_fma_f32 v[252:253], v[212:213], v[212:213], v[252:253]
	v_lshlrev_b32_e32 v214, 16, v163
	v_and_b32_e32 v215, s4, v163
	v_pk_fma_f32 v[252:253], v[214:215], v[214:215], v[252:253]
	global_store_dwordx4 v206, v[160:163], s[18:19] offset:256
	v_add_u32_e32 v206, 0x8000, v206
	s_waitcnt vmcnt(14)
	v_lshlrev_b32_e32 v208, 16, v164
	v_and_b32_e32 v209, s4, v164
	v_pk_add_f32 v[48:49], v[48:49], v[208:209]
	v_lshlrev_b32_e32 v210, 16, v165
	v_and_b32_e32 v211, s4, v165
	v_pk_add_f32 v[50:51], v[50:51], v[210:211]
	v_lshlrev_b32_e32 v208, 16, v166
	v_and_b32_e32 v209, s4, v166
	v_pk_add_f32 v[44:45], v[44:45], v[208:209]
	v_lshlrev_b32_e32 v210, 16, v167
	v_and_b32_e32 v211, s4, v167
	v_pk_add_f32 v[46:47], v[46:47], v[210:211]
	v_cvt_pk_bf16_f32 v164, v48, v49
	v_cvt_pk_bf16_f32 v165, v50, v51
	v_cvt_pk_bf16_f32 v166, v44, v45
	v_cvt_pk_bf16_f32 v167, v46, v47
	v_lshlrev_b32_e32 v212, 16, v164
	v_and_b32_e32 v213, s4, v164
	v_pk_fma_f32 v[2:3], v[212:213], v[212:213], v[2:3]
	v_lshlrev_b32_e32 v214, 16, v165
	v_and_b32_e32 v215, s4, v165
	v_pk_fma_f32 v[2:3], v[214:215], v[214:215], v[2:3]
	v_lshlrev_b32_e32 v212, 16, v166
	v_and_b32_e32 v213, s4, v166
	v_pk_fma_f32 v[2:3], v[212:213], v[212:213], v[2:3]
	v_lshlrev_b32_e32 v214, 16, v167
	v_and_b32_e32 v215, s4, v167
	v_pk_fma_f32 v[2:3], v[214:215], v[214:215], v[2:3]
	global_store_dwordx4 v206, v[164:167], s[18:19]
	v_lshlrev_b32_e32 v208, 16, v176
	v_and_b32_e32 v209, s4, v176
	v_pk_add_f32 v[40:41], v[40:41], v[208:209]
	v_lshlrev_b32_e32 v210, 16, v177
	v_and_b32_e32 v211, s4, v177
	v_pk_add_f32 v[42:43], v[42:43], v[210:211]
	v_lshlrev_b32_e32 v208, 16, v178
	v_and_b32_e32 v209, s4, v178
	v_pk_add_f32 v[36:37], v[36:37], v[208:209]
	v_lshlrev_b32_e32 v210, 16, v179
	v_and_b32_e32 v211, s4, v179
	v_pk_add_f32 v[38:39], v[38:39], v[210:211]
	v_cvt_pk_bf16_f32 v176, v40, v41
	v_cvt_pk_bf16_f32 v177, v42, v43
	v_cvt_pk_bf16_f32 v178, v36, v37
	v_cvt_pk_bf16_f32 v179, v38, v39
	v_lshlrev_b32_e32 v212, 16, v176
	v_and_b32_e32 v213, s4, v176
	v_pk_fma_f32 v[2:3], v[212:213], v[212:213], v[2:3]
	v_lshlrev_b32_e32 v214, 16, v177
	v_and_b32_e32 v215, s4, v177
	v_pk_fma_f32 v[2:3], v[214:215], v[214:215], v[2:3]
	v_lshlrev_b32_e32 v212, 16, v178
	v_and_b32_e32 v213, s4, v178
	v_pk_fma_f32 v[2:3], v[212:213], v[212:213], v[2:3]
	v_lshlrev_b32_e32 v214, 16, v179
	v_and_b32_e32 v215, s4, v179
	v_pk_fma_f32 v[2:3], v[214:215], v[214:215], v[2:3]
	global_store_dwordx4 v206, v[176:179], s[18:19] offset:256
	v_add_u32_e32 v206, 0x8000, v206
	s_waitcnt vmcnt(14)
; __device__ __forceinline__ unsigned cvt_pk_bf16(float lo, float hi) { unsigned r; asm volatile("v_cvt_pk_bf16_f32 %0, %1, %2" : "=v"(r) : "v"(lo), "v"(hi)); return r; }
;     __device__ __forceinline__ void operator()(const f32x4 (&acc)[2][2][4][2], const Unit& u, int wr, int wc, int fr, int fq) const {
;     ...
;                 for (int bj = 0; bj < 2; ++bj) { const u32x4 b = bb[ai][m][bj];
;                     const f32x4 v0 = acc[ai][bj][m][0] + (f32x4){bflo(b.x), bfhi(b.x), bflo(b.y), bfhi(b.y)}, v1 = acc[ai][bj][m][1] + (f32x4){bflo(b.z), bfhi(b.z), bflo(b.w), bfhi(b.w)};
;                     u32x4 w; w.x = cvt_pk_bf16(v0[0], v0[1]); w.y = cvt_pk_bf16(v0[2], v0[3]); w.z = cvt_pk_bf16(v1[0], v1[1]); w.w = cvt_pk_bf16(v1[2], v1[3]);
;                     *(u32x4*)(xb + off + bj * HALF) = w;
;                     const float r0 = bflo(w.x), r1 = bfhi(w.x), r2 = bflo(w.y), r3 = bfhi(w.y), r4 = bflo(w.z), r5 = bfhi(w.z), r6 = bflo(w.w), r7 = bfhi(w.w);
;                     sq += ((r0 * r0 + r1 * r1) + (r2 * r2 + r3 * r3)) + ((r4 * r4 + r5 * r5) + (r6 * r6 + r7 * r7)); }
;                 sq += __shfl_xor(sq, 16); sq += __shfl_xor(sq, 32);
;                 if (fq == 0) part[(ai * HALF + wr * 64 + m * 16 + fr) * 4 + wc] = sq; }
	v_lshlrev_b32_e32 v208, 16, v180
	v_and_b32_e32 v209, s4, v180
	v_pk_add_f32 v[32:33], v[32:33], v[208:209]
	v_lshlrev_b32_e32 v210, 16, v181
	v_and_b32_e32 v211, s4, v181
	v_pk_add_f32 v[34:35], v[34:35], v[210:211]
	v_lshlrev_b32_e32 v208, 16, v182
	v_and_b32_e32 v209, s4, v182
	v_pk_add_f32 v[28:29], v[28:29], v[208:209]
	v_lshlrev_b32_e32 v210, 16, v183
	v_and_b32_e32 v211, s4, v183
	v_pk_add_f32 v[30:31], v[30:31], v[210:211]
	v_cvt_pk_bf16_f32 v180, v32, v33
	v_cvt_pk_bf16_f32 v181, v34, v35
	v_cvt_pk_bf16_f32 v182, v28, v29
	v_cvt_pk_bf16_f32 v183, v30, v31
	v_lshlrev_b32_e32 v212, 16, v180
	v_and_b32_e32 v213, s4, v180
	v_pk_fma_f32 v[192:193], v[212:213], v[212:213], v[192:193]
	v_lshlrev_b32_e32 v214, 16, v181
	v_and_b32_e32 v215, s4, v181
	v_pk_fma_f32 v[192:193], v[214:215], v[214:215], v[192:193]
	v_lshlrev_b32_e32 v212, 16, v182
	v_and_b32_e32 v213, s4, v182
	v_pk_fma_f32 v[192:193], v[212:213], v[212:213], v[192:193]
	v_lshlrev_b32_e32 v214, 16, v183
	v_and_b32_e32 v215, s4, v183
	v_pk_fma_f32 v[192:193], v[214:215], v[214:215], v[192:193]
	global_store_dwordx4 v206, v[180:183], s[18:19]
	v_lshlrev_b32_e32 v208, 16, v184
	v_and_b32_e32 v209, s4, v184
	v_pk_add_f32 v[24:25], v[24:25], v[208:209]
	v_lshlrev_b32_e32 v210, 16, v185
	v_and_b32_e32 v211, s4, v185
	v_pk_add_f32 v[26:27], v[26:27], v[210:211]
	v_lshlrev_b32_e32 v208, 16, v186
	v_and_b32_e32 v209, s4, v186
	v_pk_add_f32 v[20:21], v[20:21], v[208:209]
	v_lshlrev_b32_e32 v210, 16, v187
	v_and_b32_e32 v211, s4, v187
	v_pk_add_f32 v[22:23], v[22:23], v[210:211]
	v_cvt_pk_bf16_f32 v184, v24, v25
	v_cvt_pk_bf16_f32 v185, v26, v27
	v_cvt_pk_bf16_f32 v186, v20, v21
	v_cvt_pk_bf16_f32 v187, v22, v23
	v_lshlrev_b32_e32 v212, 16, v184
	v_and_b32_e32 v213, s4, v184
	v_pk_fma_f32 v[192:193], v[212:213], v[212:213], v[192:193]
	v_lshlrev_b32_e32 v214, 16, v185
	v_and_b32_e32 v215, s4, v185
	v_pk_fma_f32 v[192:193], v[214:215], v[214:215], v[192:193]
	v_lshlrev_b32_e32 v212, 16, v186
	v_and_b32_e32 v213, s4, v186
	v_pk_fma_f32 v[192:193], v[212:213], v[212:213], v[192:193]
	v_lshlrev_b32_e32 v214, 16, v187
	v_and_b32_e32 v215, s4, v187
	v_pk_fma_f32 v[192:193], v[214:215], v[214:215], v[192:193]
	global_store_dwordx4 v206, v[184:187], s[18:19] offset:256
	v_add_u32_e32 v206, 0x8000, v206
	s_waitcnt vmcnt(14)
	v_lshlrev_b32_e32 v208, 16, v188
	v_and_b32_e32 v209, s4, v188
	v_pk_add_f32 v[16:17], v[16:17], v[208:209]
	v_lshlrev_b32_e32 v210, 16, v189
	v_and_b32_e32 v211, s4, v189
	v_pk_add_f32 v[18:19], v[18:19], v[210:211]
	v_lshlrev_b32_e32 v208, 16, v190
	v_and_b32_e32 v209, s4, v190
	v_pk_add_f32 v[12:13], v[12:13], v[208:209]
	v_lshlrev_b32_e32 v210, 16, v191
	v_and_b32_e32 v211, s4, v191
	v_pk_add_f32 v[14:15], v[14:15], v[210:211]
	v_cvt_pk_bf16_f32 v188, v16, v17
	v_cvt_pk_bf16_f32 v189, v18, v19
	v_cvt_pk_bf16_f32 v190, v12, v13
	v_cvt_pk_bf16_f32 v191, v14, v15
	v_lshlrev_b32_e32 v212, 16, v188
	v_and_b32_e32 v213, s4, v188
	v_pk_fma_f32 v[172:173], v[212:213], v[212:213], v[172:173]
	v_lshlrev_b32_e32 v214, 16, v189
	v_and_b32_e32 v215, s4, v189
	v_pk_fma_f32 v[172:173], v[214:215], v[214:215], v[172:173]
	v_lshlrev_b32_e32 v212, 16, v190
	v_and_b32_e32 v213, s4, v190
	v_pk_fma_f32 v[172:173], v[212:213], v[212:213], v[172:173]
	v_lshlrev_b32_e32 v214, 16, v191
	v_and_b32_e32 v215, s4, v191
	v_pk_fma_f32 v[172:173], v[214:215], v[214:215], v[172:173]
	global_store_dwordx4 v206, v[188:191], s[18:19]
	v_lshlrev_b32_e32 v208, 16, v202
	v_and_b32_e32 v209, s4, v202
	v_pk_add_f32 v[8:9], v[8:9], v[208:209]
	v_lshlrev_b32_e32 v210, 16, v203
	v_and_b32_e32 v211, s4, v203
	v_pk_add_f32 v[10:11], v[10:11], v[210:211]
	v_lshlrev_b32_e32 v208, 16, v204
	v_and_b32_e32 v209, s4, v204
	v_pk_add_f32 v[4:5], v[4:5], v[208:209]
	v_lshlrev_b32_e32 v210, 16, v205
	v_and_b32_e32 v211, s4, v205
	v_pk_add_f32 v[6:7], v[6:7], v[210:211]
	v_cvt_pk_bf16_f32 v202, v8, v9
	v_cvt_pk_bf16_f32 v203, v10, v11
	v_cvt_pk_bf16_f32 v204, v4, v5
	v_cvt_pk_bf16_f32 v205, v6, v7
	v_lshlrev_b32_e32 v212, 16, v202
	v_and_b32_e32 v213, s4, v202
	v_pk_fma_f32 v[172:173], v[212:213], v[212:213], v[172:173]
	v_lshlrev_b32_e32 v214, 16, v203
	v_and_b32_e32 v215, s4, v203
	v_pk_fma_f32 v[172:173], v[214:215], v[214:215], v[172:173]
	v_lshlrev_b32_e32 v212, 16, v204
	v_and_b32_e32 v213, s4, v204
	v_pk_fma_f32 v[172:173], v[212:213], v[212:213], v[172:173]
	v_lshlrev_b32_e32 v214, 16, v205
	v_and_b32_e32 v215, s4, v205
	v_pk_fma_f32 v[172:173], v[214:215], v[214:215], v[172:173]
	global_store_dwordx4 v206, v[202:205], s[18:19] offset:256
	v_add_f32_e32 v216, v216, v217
	v_add_f32_e32 v218, v218, v219
	v_add_f32_e32 v248, v248, v249
	v_add_f32_e32 v250, v250, v251
	v_add_f32_e32 v252, v252, v253
	v_add_f32_e32 v2, v2, v3
	v_add_f32_e32 v192, v192, v193
	v_add_f32_e32 v172, v172, v173
	v_xor_b32_e32 v174, 16, v226
	v_xor_b32_e32 v175, 32, v226
	v_lshlrev_b32_e32 v174, 2, v174
	v_lshlrev_b32_e32 v175, 2, v175
	ds_bpermute_b32 v168, v174, v216
	ds_bpermute_b32 v169, v174, v218
	ds_bpermute_b32 v170, v174, v248
	ds_bpermute_b32 v171, v174, v250
	ds_bpermute_b32 v140, v174, v252
	ds_bpermute_b32 v141, v174, v2
	ds_bpermute_b32 v142, v174, v192
	ds_bpermute_b32 v143, v174, v172
	s_waitcnt lgkmcnt(0)
	v_add_f32_e32 v216, v216, v168
	v_add_f32_e32 v218, v218, v169
	v_add_f32_e32 v248, v248, v170
	v_add_f32_e32 v250, v250, v171
	v_add_f32_e32 v252, v252, v140
	v_add_f32_e32 v2, v2, v141
	v_add_f32_e32 v192, v192, v142
	v_add_f32_e32 v172, v172, v143
	ds_bpermute_b32 v168, v175, v216
	ds_bpermute_b32 v169, v175, v218
	ds_bpermute_b32 v170, v175, v248
	ds_bpermute_b32 v171, v175, v250
	ds_bpermute_b32 v140, v175, v252
	ds_bpermute_b32 v141, v175, v2
	ds_bpermute_b32 v142, v175, v192
	ds_bpermute_b32 v143, v175, v172
	s_waitcnt lgkmcnt(0)
	v_add_f32_e32 v216, v216, v168
	v_add_f32_e32 v218, v218, v169
	v_add_f32_e32 v248, v248, v170
	v_add_f32_e32 v250, v250, v171
	v_add_f32_e32 v252, v252, v140
	v_add_f32_e32 v2, v2, v141
	v_add_f32_e32 v192, v192, v142
	v_add_f32_e32 v172, v172, v143
	s_and_saveexec_b64 s[4:5], s[6:7]
	ds_write_b32 v246, v216
	ds_write_b32 v246, v218 offset:256
	ds_write_b32 v246, v248 offset:512
	ds_write_b32 v246, v250 offset:768
	ds_write_b32 v246, v252 offset:2048
	ds_write_b32 v246, v2 offset:2304
	ds_write_b32 v246, v192 offset:2560
	ds_write_b32 v246, v172 offset:2816
